# grid barrier first-use census: the 16 device-scope counter loads of a sweep issued together instead of one round trip each
# speedup vs baseline: 1.0139x; 1.0139x over previous
.LBB0_1156:
	v_readlane_b32 s4, v251, 9
	v_readlane_b32 s5, v251, 10
	v_readlane_b32 s18, v254, 54
	s_mov_b64 s[36:37], -1
	s_waitcnt lgkmcnt(0)
	s_nop 1
	global_load_dword v0, v64, s[4:5] sc1
	v_readlane_b32 s4, v251, 11
	v_readlane_b32 s5, v251, 12
	s_nop 4
	global_load_dword v1, v64, s[4:5] sc1
	v_readlane_b32 s4, v251, 13
	v_readlane_b32 s5, v251, 14
	s_nop 4
	global_load_dword v2, v64, s[4:5] sc1
	v_readlane_b32 s4, v251, 15
	v_readlane_b32 s5, v251, 16
	s_nop 4
	global_load_dword v3, v64, s[4:5] sc1
	v_readlane_b32 s4, v251, 17
	v_readlane_b32 s5, v251, 18
	s_nop 4
	global_load_dword v4, v64, s[4:5] sc1
	v_readlane_b32 s4, v251, 19
	v_readlane_b32 s5, v251, 20
	s_nop 4
	global_load_dword v5, v64, s[4:5] sc1
	v_readlane_b32 s4, v251, 21
	v_readlane_b32 s5, v251, 22
	s_nop 4
	global_load_dword v6, v64, s[4:5] sc1
	v_readlane_b32 s4, v251, 23
	v_readlane_b32 s5, v251, 24
	s_nop 4
	global_load_dword v7, v64, s[4:5] sc1
	v_readlane_b32 s4, v251, 25
	v_readlane_b32 s5, v251, 26
	s_nop 4
	global_load_dword v8, v64, s[4:5] sc1
	v_readlane_b32 s4, v251, 27
	v_readlane_b32 s5, v251, 28
	s_nop 4
	global_load_dword v9, v64, s[4:5] sc1
	v_readlane_b32 s4, v251, 29
	v_readlane_b32 s5, v251, 30
	s_nop 4
	global_load_dword v10, v64, s[4:5] sc1
	v_readlane_b32 s4, v251, 31
	v_readlane_b32 s5, v251, 32
	s_nop 4
	global_load_dword v11, v64, s[4:5] sc1
	v_readlane_b32 s4, v251, 33
	v_readlane_b32 s5, v251, 34
	s_nop 4
	global_load_dword v12, v64, s[4:5] sc1
	v_readlane_b32 s4, v251, 35
	v_readlane_b32 s5, v251, 36
	s_nop 4
	global_load_dword v13, v64, s[4:5] sc1
	v_readlane_b32 s4, v251, 37
	v_readlane_b32 s5, v251, 38
	s_nop 4
	global_load_dword v14, v64, s[4:5] sc1
	v_readlane_b32 s4, v251, 39
	v_readlane_b32 s5, v251, 40
	s_nop 4
	global_load_dword v15, v64, s[4:5] sc1
	s_mov_b64 s[4:5], -1
	s_waitcnt vmcnt(0)
	v_add_u32_e32 v16, v1, v0
	v_add_u32_e32 v16, v16, v2
	v_add_u32_e32 v16, v16, v3
	v_add_u32_e32 v16, v16, v4
	v_add_u32_e32 v16, v16, v5
	v_add_u32_e32 v16, v16, v6
	v_add_u32_e32 v16, v16, v7
	v_add_u32_e32 v16, v16, v8
	v_add_u32_e32 v16, v16, v9
	v_add_u32_e32 v16, v16, v10
	v_add_u32_e32 v16, v16, v11
	v_add_u32_e32 v16, v16, v12
	v_add_u32_e32 v16, v16, v13
	v_add_u32_e32 v16, v16, v14
	v_add_u32_e32 v16, v16, v15
	v_cmp_eq_u32_e32 vcc, s18, v16
	s_cbranch_vccnz .LBB0_1155
	s_and_b32 s4, s10, 0xff
	s_cmp_eq_u32 s4, 0
	s_mov_b64 s[4:5], -1
	s_mov_b64 s[38:39], -1
	s_sleep 1
	s_cbranch_scc0 .LBB0_1160
	v_readlane_b32 s4, v251, 7
	v_readlane_b32 s5, v251, 8
	s_nop 4
	global_load_dword v16, v64, s[4:5] sc1
	s_waitcnt vmcnt(0)
	v_cmp_eq_u32_e32 vcc, 0, v16
	s_cbranch_vccnz .LBB0_1162
	s_mov_b64 s[38:39], 0
	s_mov_b64 s[4:5], -1
